# in-stream prune: when fewer than 256 list entries lie within six octaves of the maximum (thresholds at or below zero) the bins are rebuilt over the whole key range and the cut is refined with a second
# speedup vs baseline: 1.1918x; 1.0258x over previous
.LBB0_144:
	s_and_b32 s2, s7, 3
	v_cmp_eq_u32_e32 vcc, s2, v43
	s_and_saveexec_b64 s[2:3], vcc
	s_cbranch_execz .LBB0_143
	s_ff1_i32_b32 s8, s6
	s_mul_i32 s9, s8, 0xc00
	s_mul_i32 s10, s8, 0x600
	s_add_i32 s10, s10, 0x18000
	s_lshl_b32 s11, s8, 2
	s_add_i32 s11, s11, 0x24000
	v_mov_b32_e32 v40, s11
	ds_read_b32 v92, v40
	s_waitcnt lgkmcnt(0)
	v_readfirstlane_b32 s12, v92
	s_add_i32 s13, s12, -1
	v_min_u32_e32 v93, s13, v190
	v_lshl_add_u32 v94, v93, 2, s9
	v_lshl_add_u32 v93, v93, 1, s10
	ds_read_b32 v161, v94
	ds_read_u16 v142, v93
	v_min_u32_e32 v95, s13, v185
	v_lshl_add_u32 v120, v95, 2, s9
	v_lshl_add_u32 v95, v95, 1, s10
	ds_read_b32 v162, v120
	ds_read_u16 v143, v95
	v_min_u32_e32 v93, s13, v192
	v_lshl_add_u32 v94, v93, 2, s9
	v_lshl_add_u32 v93, v93, 1, s10
	ds_read_b32 v163, v94
	ds_read_u16 v144, v93
	v_min_u32_e32 v95, s13, v191
	v_lshl_add_u32 v120, v95, 2, s9
	v_lshl_add_u32 v95, v95, 1, s10
	ds_read_b32 v164, v120
	ds_read_u16 v145, v95
	v_min_u32_e32 v93, s13, v0
	v_lshl_add_u32 v94, v93, 2, s9
	v_lshl_add_u32 v93, v93, 1, s10
	ds_read_b32 v165, v94
	ds_read_u16 v146, v93
	v_min_u32_e32 v95, s13, v1
	v_lshl_add_u32 v120, v95, 2, s9
	v_lshl_add_u32 v95, v95, 1, s10
	ds_read_b32 v166, v120
	ds_read_u16 v148, v95
	v_min_u32_e32 v93, s13, v2
	v_lshl_add_u32 v94, v93, 2, s9
	v_lshl_add_u32 v93, v93, 1, s10
	ds_read_b32 v167, v94
	ds_read_u16 v149, v93
	v_min_u32_e32 v95, s13, v3
	v_lshl_add_u32 v120, v95, 2, s9
	v_lshl_add_u32 v95, v95, 1, s10
	ds_read_b32 v168, v120
	ds_read_u16 v150, v95
	v_min_u32_e32 v93, s13, v6
	v_lshl_add_u32 v94, v93, 2, s9
	v_lshl_add_u32 v93, v93, 1, s10
	ds_read_b32 v169, v94
	ds_read_u16 v152, v93
	v_min_u32_e32 v95, s13, v7
	v_lshl_add_u32 v120, v95, 2, s9
	v_lshl_add_u32 v95, v95, 1, s10
	ds_read_b32 v170, v120
	ds_read_u16 v153, v95
	v_min_u32_e32 v93, s13, v4
	v_lshl_add_u32 v94, v93, 2, s9
	v_lshl_add_u32 v93, v93, 1, s10
	ds_read_b32 v171, v94
	ds_read_u16 v159, v93
	v_min_u32_e32 v95, s13, v5
	v_lshl_add_u32 v120, v95, 2, s9
	v_lshl_add_u32 v95, v95, 1, s10
	ds_read_b32 v172, v120
	ds_read_u16 v160, v95
	ds_write_b128 v127, a[206:209]
	s_waitcnt lgkmcnt(1)
	v_ashrrev_i32_e32 v93, 31, v161
	v_or_b32_e32 v93, 0x80000000, v93
	v_xor_b32_e32 v108, v161, v93
	v_ashrrev_i32_e32 v94, 31, v162
	v_or_b32_e32 v94, 0x80000000, v94
	v_xor_b32_e32 v109, v162, v94
	v_ashrrev_i32_e32 v93, 31, v163
	v_or_b32_e32 v93, 0x80000000, v93
	v_xor_b32_e32 v110, v163, v93
	v_ashrrev_i32_e32 v94, 31, v164
	v_or_b32_e32 v94, 0x80000000, v94
	v_xor_b32_e32 v111, v164, v94
	v_ashrrev_i32_e32 v93, 31, v165
	v_or_b32_e32 v93, 0x80000000, v93
	v_xor_b32_e32 v112, v165, v93
	v_ashrrev_i32_e32 v94, 31, v166
	v_or_b32_e32 v94, 0x80000000, v94
	v_xor_b32_e32 v113, v166, v94
	v_ashrrev_i32_e32 v93, 31, v167
	v_or_b32_e32 v93, 0x80000000, v93
	v_xor_b32_e32 v114, v167, v93
	v_ashrrev_i32_e32 v94, 31, v168
	v_or_b32_e32 v94, 0x80000000, v94
	v_xor_b32_e32 v115, v168, v94
	v_ashrrev_i32_e32 v93, 31, v169
	v_or_b32_e32 v93, 0x80000000, v93
	v_xor_b32_e32 v116, v169, v93
	v_ashrrev_i32_e32 v94, 31, v170
	v_or_b32_e32 v94, 0x80000000, v94
	v_xor_b32_e32 v117, v170, v94
	v_ashrrev_i32_e32 v93, 31, v171
	v_or_b32_e32 v93, 0x80000000, v93
	v_xor_b32_e32 v118, v171, v93
	v_ashrrev_i32_e32 v94, 31, v172
	v_or_b32_e32 v94, 0x80000000, v94
	v_xor_b32_e32 v119, v172, v94
	v_max3_u32 v92, v108, v109, v110
	v_min3_u32 v93, v108, v109, v110
	v_max3_u32 v92, v111, v112, v92
	v_min3_u32 v93, v111, v112, v93
	v_max3_u32 v92, v113, v114, v92
	v_min3_u32 v93, v113, v114, v93
	v_max3_u32 v92, v115, v116, v92
	v_min3_u32 v93, v115, v116, v93
	v_max3_u32 v92, v117, v118, v92
	v_min3_u32 v93, v117, v118, v93
	v_max_u32_e32 v92, v119, v92
	v_min_u32_e32 v93, v119, v93
	s_nop 0
	v_max_u32_dpp v92, v92, v92 quad_perm:[1,0,3,2] row_mask:0xf bank_mask:0xf bound_ctrl:1
	v_min_u32_dpp v93, v93, v93 quad_perm:[1,0,3,2] row_mask:0xf bank_mask:0xf bound_ctrl:1
	s_nop 0
	v_max_u32_dpp v92, v92, v92 quad_perm:[2,3,0,1] row_mask:0xf bank_mask:0xf bound_ctrl:1
	v_min_u32_dpp v93, v93, v93 quad_perm:[2,3,0,1] row_mask:0xf bank_mask:0xf bound_ctrl:1
	s_nop 0
	v_max_u32_dpp v92, v92, v92 row_half_mirror row_mask:0xf bank_mask:0xf bound_ctrl:1
	v_min_u32_dpp v93, v93, v93 row_half_mirror row_mask:0xf bank_mask:0xf bound_ctrl:1
	s_nop 0
	v_max_u32_dpp v92, v92, v92 row_mirror row_mask:0xf bank_mask:0xf bound_ctrl:1
	v_min_u32_dpp v93, v93, v93 row_mirror row_mask:0xf bank_mask:0xf bound_ctrl:1
	s_nop 1
	v_readlane_b32 s15, v92, 0
	v_readlane_b32 s16, v92, 16
	v_readlane_b32 s17, v92, 32
	v_readlane_b32 s18, v92, 48
	s_max_u32 s15, s15, s16
	s_max_u32 s17, s17, s18
	s_max_u32 s15, s15, s17
	v_readlane_b32 s16, v93, 0
	v_readlane_b32 s17, v93, 16
	v_readlane_b32 s18, v93, 32
	v_readlane_b32 s19, v93, 48
	s_min_u32 s16, s16, s17
	s_min_u32 s18, s18, s19
	s_min_u32 s16, s16, s18
	s_sub_u32 s17, s15, 0x3000000
	s_cselect_b32 s17, 0, s17
	s_mov_b32 s25, s16
	s_max_u32 s14, s16, s17
.Lpr_rebin:
	s_sub_u32 s16, s15, s14
	s_add_u32 s16, s16, 1
	s_cmpk_le_u32 s16, 0x100
	s_cbranch_scc1 .Lpr_orig
	v_mov_b32_e32 v92, s16
	v_cvt_f32_u32_e32 v92, v92
	v_rcp_f32_e32 v92, v92
	s_nop 0
	v_mul_f32_e32 v92, 0x53800000, v92
	v_cvt_u32_f32_e32 v92, v92
	s_nop 0
	v_readfirstlane_b32 s21, v92
	s_nop 1
	v_max_u32_e32 v93, s14, v108
	v_subrev_u32_e32 v93, s14, v93
	v_mul_hi_u32 v93, v93, s21
	v_min_u32_e32 v173, 0xff, v93
	v_max_u32_e32 v94, s14, v109
	v_subrev_u32_e32 v94, s14, v94
	v_mul_hi_u32 v94, v94, s21
	v_min_u32_e32 v174, 0xff, v94
	v_max_u32_e32 v95, s14, v110
	v_subrev_u32_e32 v95, s14, v95
	v_mul_hi_u32 v95, v95, s21
	v_min_u32_e32 v175, 0xff, v95
	v_max_u32_e32 v93, s14, v111
	v_subrev_u32_e32 v93, s14, v93
	v_mul_hi_u32 v93, v93, s21
	v_min_u32_e32 v176, 0xff, v93
	v_max_u32_e32 v94, s14, v112
	v_subrev_u32_e32 v94, s14, v94
	v_mul_hi_u32 v94, v94, s21
	v_min_u32_e32 v177, 0xff, v94
	v_max_u32_e32 v95, s14, v113
	v_subrev_u32_e32 v95, s14, v95
	v_mul_hi_u32 v95, v95, s21
	v_min_u32_e32 v178, 0xff, v95
	v_max_u32_e32 v93, s14, v114
	v_subrev_u32_e32 v93, s14, v93
	v_mul_hi_u32 v93, v93, s21
	v_min_u32_e32 v179, 0xff, v93
	v_max_u32_e32 v94, s14, v115
	v_subrev_u32_e32 v94, s14, v94
	v_mul_hi_u32 v94, v94, s21
	v_min_u32_e32 v180, 0xff, v94
	v_max_u32_e32 v95, s14, v116
	v_subrev_u32_e32 v95, s14, v95
	v_mul_hi_u32 v95, v95, s21
	v_min_u32_e32 v181, 0xff, v95
	v_max_u32_e32 v93, s14, v117
	v_subrev_u32_e32 v93, s14, v93
	v_mul_hi_u32 v93, v93, s21
	v_min_u32_e32 v182, 0xff, v93
	v_max_u32_e32 v94, s14, v118
	v_subrev_u32_e32 v94, s14, v94
	v_mul_hi_u32 v94, v94, s21
	v_min_u32_e32 v183, 0xff, v94
	v_max_u32_e32 v95, s14, v119
	v_subrev_u32_e32 v95, s14, v95
	v_mul_hi_u32 v95, v95, s21
	v_min_u32_e32 v184, 0xff, v95
	v_cmp_gt_u32_e64 s[26:27], s12, v6
	v_cmp_gt_u32_e64 s[28:29], s12, v7
	v_cmp_gt_u32_e64 s[30:31], s12, v4
	v_cndmask_b32_e64 v181, 0, v181, s[26:27]
	v_cmp_gt_u32_e64 s[26:27], s12, v5
	v_cndmask_b32_e64 v182, 0, v182, s[28:29]
	s_nop 0
	v_cndmask_b32_e64 v183, 0, v183, s[30:31]
	v_cndmask_b32_e64 v184, 0, v184, s[26:27]
	s_mov_b64 s[22:23], exec
	v_cmp_ne_u32_e64 s[26:27], 0, v173
	v_lshl_add_u32 v93, v173, 2, v121
	s_mov_b64 exec, s[26:27]
	ds_add_u32 v93, v252
	s_mov_b64 exec, s[22:23]
	v_cmp_ne_u32_e64 s[28:29], 0, v174
	v_lshl_add_u32 v94, v174, 2, v121
	s_mov_b64 exec, s[28:29]
	ds_add_u32 v94, v252
	s_mov_b64 exec, s[22:23]
	v_cmp_ne_u32_e64 s[30:31], 0, v175
	v_lshl_add_u32 v95, v175, 2, v121
	s_mov_b64 exec, s[30:31]
	ds_add_u32 v95, v252
	s_mov_b64 exec, s[22:23]
	v_cmp_ne_u32_e64 s[26:27], 0, v176
	v_lshl_add_u32 v93, v176, 2, v121
	s_mov_b64 exec, s[26:27]
	ds_add_u32 v93, v252
	s_mov_b64 exec, s[22:23]
	v_cmp_ne_u32_e64 s[28:29], 0, v177
	v_lshl_add_u32 v94, v177, 2, v121
	s_mov_b64 exec, s[28:29]
	ds_add_u32 v94, v252
	s_mov_b64 exec, s[22:23]
	v_cmp_ne_u32_e64 s[30:31], 0, v178
	v_lshl_add_u32 v95, v178, 2, v121
	s_mov_b64 exec, s[30:31]
	ds_add_u32 v95, v252
	s_mov_b64 exec, s[22:23]
	v_cmp_ne_u32_e64 s[26:27], 0, v179
	v_lshl_add_u32 v93, v179, 2, v121
	s_mov_b64 exec, s[26:27]
	ds_add_u32 v93, v252
	s_mov_b64 exec, s[22:23]
	v_cmp_ne_u32_e64 s[28:29], 0, v180
	v_lshl_add_u32 v94, v180, 2, v121
	s_mov_b64 exec, s[28:29]
	ds_add_u32 v94, v252
	s_mov_b64 exec, s[22:23]
	v_cmp_ne_u32_e64 s[30:31], 0, v181
	v_lshl_add_u32 v95, v181, 2, v121
	s_mov_b64 exec, s[30:31]
	ds_add_u32 v95, v252
	s_mov_b64 exec, s[22:23]
	v_cmp_ne_u32_e64 s[26:27], 0, v182
	v_lshl_add_u32 v93, v182, 2, v121
	s_mov_b64 exec, s[26:27]
	ds_add_u32 v93, v252
	s_mov_b64 exec, s[22:23]
	v_cmp_ne_u32_e64 s[28:29], 0, v183
	v_lshl_add_u32 v94, v183, 2, v121
	s_mov_b64 exec, s[28:29]
	ds_add_u32 v94, v252
	s_mov_b64 exec, s[22:23]
	v_cmp_ne_u32_e64 s[30:31], 0, v184
	v_lshl_add_u32 v95, v184, 2, v121
	s_mov_b64 exec, s[30:31]
	ds_add_u32 v95, v252
	s_mov_b64 exec, s[22:23]
	ds_read_b128 v[92:95], v127
	s_waitcnt lgkmcnt(0)
	v_add_u32_e32 v120, v92, v93
	v_add3_u32 v120, v120, v94, v95
	v_mov_b32_e32 v122, v120
	s_nop 1
	v_add_u32_dpp v122, v122, v122 row_shr:1 row_mask:0xf bank_mask:0xf bound_ctrl:1
	s_nop 1
	v_add_u32_dpp v122, v122, v122 row_shr:2 row_mask:0xf bank_mask:0xf bound_ctrl:1
	s_nop 1
	v_add_u32_dpp v122, v122, v122 row_shr:4 row_mask:0xf bank_mask:0xf bound_ctrl:1
	s_nop 1
	v_add_u32_dpp v122, v122, v122 row_shr:8 row_mask:0xf bank_mask:0xf bound_ctrl:1
	s_nop 1
	v_add_u32_dpp v122, v122, v122 row_bcast:15 row_mask:0xa bank_mask:0xf
	s_nop 1
	v_add_u32_dpp v122, v122, v122 row_bcast:31 row_mask:0xc bank_mask:0xf
	s_nop 1
	v_readlane_b32 s16, v122, 63
	s_nop 1
	v_sub_u32_e32 v123, s16, v122
	v_add_u32_e32 v124, v123, v95
	v_add_u32_e32 v126, v124, v94
	v_add_u32_e32 v128, v126, v93
	v_add_u32_e32 v129, v128, v92
	s_movk_i32 s17, 0x100
	v_lshlrev_b32_e32 v130, 2, v190
	v_cmp_le_u32_e64 s[26:27], s17, v128
	v_cmp_le_u32_e64 s[28:29], s17, v126
	v_cmp_le_u32_e64 s[30:31], s17, v124
	v_mov_b32_e32 v134, v130
	v_or_b32_e32 v131, 1, v134
	v_cndmask_b32_e64 v129, v129, v128, s[26:27]
	v_cndmask_b32_e64 v130, v130, v131, s[26:27]
	v_or_b32_e32 v131, 2, v134
	v_cndmask_b32_e64 v129, v129, v126, s[28:29]
	v_cndmask_b32_e64 v130, v130, v131, s[28:29]
	v_or_b32_e32 v131, 3, v134
	v_cndmask_b32_e64 v129, v129, v124, s[30:31]
	v_cndmask_b32_e64 v130, v130, v131, s[30:31]
	v_add_u32_e32 v132, v123, v120
	v_cmp_gt_u32_e64 s[26:27], s17, v123
	v_cmp_le_u32_e64 s[28:29], s17, v132
	s_nop 0
	s_and_b64 s[26:27], s[26:27], s[28:29]
	s_cmp_eq_u64 s[26:27], 0
	s_cbranch_scc1 .Lpr_retry
	s_ff1_i32_b64 s18, s[26:27]
	s_nop 3
	v_readlane_b32 s19, v129, s18
	v_readlane_b32 s20, v130, s18
	s_cmpk_gt_u32 s19, 0x140
	s_cselect_b32 s24, 1, 0
	s_cmp_eq_u32 s20, 0
	s_cbranch_scc1 .Lpr_retry
	v_mov_b32_e32 v92, s21
	v_cvt_f32_u32_e32 v92, v92
	v_rcp_f32_e32 v92, v92
	v_mov_b32_e32 v93, s20
	v_cvt_f32_u32_e32 v93, v93
	v_mul_f32_e32 v92, 0x4f800000, v92
	v_mul_f32_e32 v92, v92, v93
	v_mul_f32_e32 v92, 0x3f7ffff0, v92
	v_cvt_u32_f32_e32 v92, v92
	s_nop 0
	v_readfirstlane_b32 s16, v92
	s_add_u32 s16, s16, s14
	s_mov_b32 s13, s16
	s_cmp_eq_u32 s24, 0
	s_cbranch_scc1 .Lpr_noexact
	v_mov_b32_e32 v136, 0
	v_cmp_eq_u32_e64 s[26:27], s20, v173
	v_cmp_eq_u32_e64 s[28:29], s20, v174
	v_cmp_eq_u32_e64 s[30:31], s20, v175
	v_addc_co_u32_e64 v136, vcc, 0, v136, s[26:27]
	v_cmp_eq_u32_e64 s[26:27], s20, v176
	v_addc_co_u32_e64 v136, vcc, 0, v136, s[28:29]
	v_cmp_eq_u32_e64 s[28:29], s20, v177
	v_addc_co_u32_e64 v136, vcc, 0, v136, s[30:31]
	v_cmp_eq_u32_e64 s[30:31], s20, v178
	v_addc_co_u32_e64 v136, vcc, 0, v136, s[26:27]
	v_cmp_eq_u32_e64 s[26:27], s20, v179
	v_addc_co_u32_e64 v136, vcc, 0, v136, s[28:29]
	v_cmp_eq_u32_e64 s[28:29], s20, v180
	v_addc_co_u32_e64 v136, vcc, 0, v136, s[30:31]
	v_cmp_eq_u32_e64 s[30:31], s20, v181
	v_addc_co_u32_e64 v136, vcc, 0, v136, s[26:27]
	v_cmp_eq_u32_e64 s[26:27], s20, v182
	v_addc_co_u32_e64 v136, vcc, 0, v136, s[28:29]
	v_cmp_eq_u32_e64 s[28:29], s20, v183
	v_addc_co_u32_e64 v136, vcc, 0, v136, s[30:31]
	v_cmp_eq_u32_e64 s[30:31], s20, v184
	v_addc_co_u32_e64 v136, vcc, 0, v136, s[26:27]
	s_nop 0
	v_addc_co_u32_e64 v136, vcc, 0, v136, s[28:29]
	v_addc_co_u32_e64 v136, vcc, 0, v136, s[30:31]
	s_nop 1
	v_add_u32_dpp v136, v136, v136 quad_perm:[1,0,3,2] row_mask:0xf bank_mask:0xf bound_ctrl:1
	s_nop 1
	v_add_u32_dpp v136, v136, v136 quad_perm:[2,3,0,1] row_mask:0xf bank_mask:0xf bound_ctrl:1
	s_nop 1
	v_add_u32_dpp v136, v136, v136 row_half_mirror row_mask:0xf bank_mask:0xf bound_ctrl:1
	s_nop 1
	v_add_u32_dpp v136, v136, v136 row_mirror row_mask:0xf bank_mask:0xf bound_ctrl:1
	s_nop 1
	v_readlane_b32 s14, v136, 0
	v_readlane_b32 s15, v136, 16
	v_readlane_b32 s17, v136, 32
	v_readlane_b32 s18, v136, 48
	s_add_i32 s14, s14, s15
	s_add_i32 s17, s17, s18
	s_add_i32 s14, s14, s17
	s_sub_i32 s15, s19, s14
	s_sub_i32 s15, 0x100, s15
	s_sub_i32 s25, s14, s15
	v_mov_b32_e32 v92, s21
	v_cvt_f32_u32_e32 v92, v92
	v_rcp_f32_e32 v92, v92
	s_nop 0
	v_mul_f32_e32 v92, 0x4f800000, v92
	v_mul_f32_e32 v92, 0x3f800008, v92
	v_cvt_u32_f32_e32 v92, v92
	v_add_u32_e32 v92, 0x40, v92
	v_cvt_f32_u32_e32 v93, v92
	v_rcp_f32_e32 v93, v93
	s_nop 0
	v_mul_f32_e32 v93, 0x53800000, v93
	v_cvt_u32_f32_e32 v93, v93
	s_nop 0
	v_readfirstlane_b32 s17, v92
	v_readfirstlane_b32 s18, v93
	s_cmpk_le_u32 s17, 0x100
	s_cbranch_scc1 .Lpr_orig
	ds_write_b128 v127, a[206:209]
	s_mov_b64 s[22:23], exec
	v_cmp_eq_u32_e64 s[26:27], s20, v173
	v_subrev_u32_e32 v93, s13, v108
	v_mul_hi_u32 v93, v93, s18
	v_min_u32_e32 v120, 0xff, v93
	v_lshl_add_u32 v93, v120, 2, v121
	s_mov_b64 exec, s[26:27]
	ds_add_u32 v93, v252
	s_mov_b64 exec, s[22:23]
	v_cmp_eq_u32_e64 s[28:29], s20, v174
	v_subrev_u32_e32 v94, s13, v109
	v_mul_hi_u32 v94, v94, s18
	v_min_u32_e32 v122, 0xff, v94
	v_lshl_add_u32 v94, v122, 2, v121
	s_mov_b64 exec, s[28:29]
	ds_add_u32 v94, v252
	s_mov_b64 exec, s[22:23]
	v_cmp_eq_u32_e64 s[30:31], s20, v175
	v_subrev_u32_e32 v95, s13, v110
	v_mul_hi_u32 v95, v95, s18
	v_min_u32_e32 v123, 0xff, v95
	v_lshl_add_u32 v95, v123, 2, v121
	s_mov_b64 exec, s[30:31]
	ds_add_u32 v95, v252
	s_mov_b64 exec, s[22:23]
	v_cmp_eq_u32_e64 s[26:27], s20, v176
	v_subrev_u32_e32 v93, s13, v111
	v_mul_hi_u32 v93, v93, s18
	v_min_u32_e32 v124, 0xff, v93
	v_lshl_add_u32 v93, v124, 2, v121
	s_mov_b64 exec, s[26:27]
	ds_add_u32 v93, v252
	s_mov_b64 exec, s[22:23]
	v_cmp_eq_u32_e64 s[28:29], s20, v177
	v_subrev_u32_e32 v94, s13, v112
	v_mul_hi_u32 v94, v94, s18
	v_min_u32_e32 v126, 0xff, v94
	v_lshl_add_u32 v94, v126, 2, v121
	s_mov_b64 exec, s[28:29]
	ds_add_u32 v94, v252
	s_mov_b64 exec, s[22:23]
	v_cmp_eq_u32_e64 s[30:31], s20, v178
	v_subrev_u32_e32 v95, s13, v113
	v_mul_hi_u32 v95, v95, s18
	v_min_u32_e32 v128, 0xff, v95
	v_lshl_add_u32 v95, v128, 2, v121
	s_mov_b64 exec, s[30:31]
	ds_add_u32 v95, v252
	s_mov_b64 exec, s[22:23]
	v_cmp_eq_u32_e64 s[26:27], s20, v179
	v_subrev_u32_e32 v93, s13, v114
	v_mul_hi_u32 v93, v93, s18
	v_min_u32_e32 v129, 0xff, v93
	v_lshl_add_u32 v93, v129, 2, v121
	s_mov_b64 exec, s[26:27]
	ds_add_u32 v93, v252
	s_mov_b64 exec, s[22:23]
	v_cmp_eq_u32_e64 s[28:29], s20, v180
	v_subrev_u32_e32 v94, s13, v115
	v_mul_hi_u32 v94, v94, s18
	v_min_u32_e32 v130, 0xff, v94
	v_lshl_add_u32 v94, v130, 2, v121
	s_mov_b64 exec, s[28:29]
	ds_add_u32 v94, v252
	s_mov_b64 exec, s[22:23]
	v_cmp_eq_u32_e64 s[30:31], s20, v181
	v_subrev_u32_e32 v95, s13, v116
	v_mul_hi_u32 v95, v95, s18
	v_min_u32_e32 v131, 0xff, v95
	v_lshl_add_u32 v95, v131, 2, v121
	s_mov_b64 exec, s[30:31]
	ds_add_u32 v95, v252
	s_mov_b64 exec, s[22:23]
	v_cmp_eq_u32_e64 s[26:27], s20, v182
	v_subrev_u32_e32 v93, s13, v117
	v_mul_hi_u32 v93, v93, s18
	v_min_u32_e32 v132, 0xff, v93
	v_lshl_add_u32 v93, v132, 2, v121
	s_mov_b64 exec, s[26:27]
	ds_add_u32 v93, v252
	s_mov_b64 exec, s[22:23]
	v_cmp_eq_u32_e64 s[28:29], s20, v183
	v_subrev_u32_e32 v94, s13, v118
	v_mul_hi_u32 v94, v94, s18
	v_min_u32_e32 v134, 0xff, v94
	v_lshl_add_u32 v94, v134, 2, v121
	s_mov_b64 exec, s[28:29]
	ds_add_u32 v94, v252
	s_mov_b64 exec, s[22:23]
	v_cmp_eq_u32_e64 s[30:31], s20, v184
	v_subrev_u32_e32 v95, s13, v119
	v_mul_hi_u32 v95, v95, s18
	v_min_u32_e32 v135, 0xff, v95
	v_lshl_add_u32 v95, v135, 2, v121
	s_mov_b64 exec, s[30:31]
	ds_add_u32 v95, v252
	s_mov_b64 exec, s[22:23]
	ds_read_b128 v[92:95], v127
	s_waitcnt lgkmcnt(0)
	v_add_u32_e32 v136, v92, v93
	v_add3_u32 v136, v136, v94, v95
	v_mov_b32_e32 v137, v136
	s_nop 1
	v_add_u32_dpp v137, v137, v137 row_shr:1 row_mask:0xf bank_mask:0xf bound_ctrl:1
	s_nop 1
	v_add_u32_dpp v137, v137, v137 row_shr:2 row_mask:0xf bank_mask:0xf bound_ctrl:1
	s_nop 1
	v_add_u32_dpp v137, v137, v137 row_shr:4 row_mask:0xf bank_mask:0xf bound_ctrl:1
	s_nop 1
	v_add_u32_dpp v137, v137, v137 row_shr:8 row_mask:0xf bank_mask:0xf bound_ctrl:1
	s_nop 1
	v_add_u32_dpp v137, v137, v137 row_bcast:15 row_mask:0xa bank_mask:0xf
	s_nop 1
	v_add_u32_dpp v137, v137, v137 row_bcast:31 row_mask:0xc bank_mask:0xf
	s_nop 1
	v_readlane_b32 s17, v137, 63
	s_nop 1
	v_sub_u32_e32 v138, s17, v137
	v_add_u32_e32 v140, v138, v95
	v_add_u32_e32 v95, v140, v94
	v_add_u32_e32 v94, v95, v93
	v_add_u32_e32 v93, v94, v92
	v_lshlrev_b32_e32 v92, 2, v190
	v_cmp_le_u32_e64 s[26:27], s15, v94
	v_cmp_le_u32_e64 s[28:29], s15, v95
	v_cmp_le_u32_e64 s[30:31], s15, v140
	v_mov_b32_e32 v137, v92
	v_mov_b32_e32 v136, v93
	v_or_b32_e32 v93, 1, v137
	v_cndmask_b32_e64 v136, v136, v94, s[26:27]
	v_cndmask_b32_e64 v92, v92, v93, s[26:27]
	v_or_b32_e32 v93, 2, v137
	v_cndmask_b32_e64 v136, v136, v95, s[28:29]
	v_cndmask_b32_e64 v92, v92, v93, s[28:29]
	v_or_b32_e32 v93, 3, v137
	v_cndmask_b32_e64 v136, v136, v140, s[30:31]
	v_cndmask_b32_e64 v92, v92, v93, s[30:31]
	v_add_u32_e32 v94, v138, v95
	v_cmp_gt_u32_e64 s[26:27], s15, v138
	v_cmp_le_u32_e64 s[28:29], s15, v136
	s_nop 0
	s_and_b64 s[26:27], s[26:27], s[28:29]
	s_cmp_eq_u64 s[26:27], 0
	s_cbranch_scc1 .Lpr_orig
	s_ff1_i32_b64 s17, s[26:27]
	s_nop 3
	v_readlane_b32 s25, v136, s17
	v_readlane_b32 s14, v92, s17
	s_sub_i32 s25, s25, s15
	s_cmpk_gt_u32 s25, 0x90
	s_cbranch_scc1 .Lpr_orig
	v_cmp_eq_u32_e64 s[26:27], s20, v173
	v_cmp_gt_u32_e64 s[28:29], s14, v120
	s_nop 0
	s_and_b64 s[28:29], s[28:29], s[26:27]
	s_nop 1
	v_cndmask_b32_e64 v173, v173, 0, s[28:29]
	v_cmp_eq_u32_e64 s[26:27], s20, v174
	v_cmp_gt_u32_e64 s[28:29], s14, v122
	s_nop 0
	s_and_b64 s[28:29], s[28:29], s[26:27]
	s_nop 1
	v_cndmask_b32_e64 v174, v174, 0, s[28:29]
	v_cmp_eq_u32_e64 s[26:27], s20, v175
	v_cmp_gt_u32_e64 s[28:29], s14, v123
	s_nop 0
	s_and_b64 s[28:29], s[28:29], s[26:27]
	s_nop 1
	v_cndmask_b32_e64 v175, v175, 0, s[28:29]
	v_cmp_eq_u32_e64 s[26:27], s20, v176
	v_cmp_gt_u32_e64 s[28:29], s14, v124
	s_nop 0
	s_and_b64 s[28:29], s[28:29], s[26:27]
	s_nop 1
	v_cndmask_b32_e64 v176, v176, 0, s[28:29]
	v_cmp_eq_u32_e64 s[26:27], s20, v177
	v_cmp_gt_u32_e64 s[28:29], s14, v126
	s_nop 0
	s_and_b64 s[28:29], s[28:29], s[26:27]
	s_nop 1
	v_cndmask_b32_e64 v177, v177, 0, s[28:29]
	v_cmp_eq_u32_e64 s[26:27], s20, v178
	v_cmp_gt_u32_e64 s[28:29], s14, v128
	s_nop 0
	s_and_b64 s[28:29], s[28:29], s[26:27]
	s_nop 1
	v_cndmask_b32_e64 v178, v178, 0, s[28:29]
	v_cmp_eq_u32_e64 s[26:27], s20, v179
	v_cmp_gt_u32_e64 s[28:29], s14, v129
	s_nop 0
	s_and_b64 s[28:29], s[28:29], s[26:27]
	s_nop 1
	v_cndmask_b32_e64 v179, v179, 0, s[28:29]
	v_cmp_eq_u32_e64 s[26:27], s20, v180
	v_cmp_gt_u32_e64 s[28:29], s14, v130
	s_nop 0
	s_and_b64 s[28:29], s[28:29], s[26:27]
	s_nop 1
	v_cndmask_b32_e64 v180, v180, 0, s[28:29]
	v_cmp_eq_u32_e64 s[26:27], s20, v181
	v_cmp_gt_u32_e64 s[28:29], s14, v131
	s_nop 0
	s_and_b64 s[28:29], s[28:29], s[26:27]
	s_nop 1
	v_cndmask_b32_e64 v181, v181, 0, s[28:29]
	v_cmp_eq_u32_e64 s[26:27], s20, v182
	v_cmp_gt_u32_e64 s[28:29], s14, v132
	s_nop 0
	s_and_b64 s[28:29], s[28:29], s[26:27]
	s_nop 1
	v_cndmask_b32_e64 v182, v182, 0, s[28:29]
	v_cmp_eq_u32_e64 s[26:27], s20, v183
	v_cmp_gt_u32_e64 s[28:29], s14, v134
	s_nop 0
	s_and_b64 s[28:29], s[28:29], s[26:27]
	s_nop 1
	v_cndmask_b32_e64 v183, v183, 0, s[28:29]
	v_cmp_eq_u32_e64 s[26:27], s20, v184
	v_cmp_gt_u32_e64 s[28:29], s14, v135
	s_nop 0
	s_and_b64 s[28:29], s[28:29], s[26:27]
	s_nop 1
	v_cndmask_b32_e64 v184, v184, 0, s[28:29]
	s_add_i32 s19, s25, 0x100
	v_cmp_le_u32_e64 s[26:27], s20, v173
	s_nop 1
	v_cndmask_b32_e64 v93, -1, v108, s[26:27]
	v_mov_b32_e32 v92, v93
	v_cmp_le_u32_e64 s[28:29], s20, v174
	s_nop 1
	v_cndmask_b32_e64 v94, -1, v109, s[28:29]
	v_min_u32_e32 v92, v92, v94
	v_cmp_le_u32_e64 s[30:31], s20, v175
	s_nop 1
	v_cndmask_b32_e64 v95, -1, v110, s[30:31]
	v_min_u32_e32 v92, v92, v95
	v_cmp_le_u32_e64 s[26:27], s20, v176
	s_nop 1
	v_cndmask_b32_e64 v93, -1, v111, s[26:27]
	v_min_u32_e32 v92, v92, v93
	v_cmp_le_u32_e64 s[28:29], s20, v177
	s_nop 1
	v_cndmask_b32_e64 v94, -1, v112, s[28:29]
	v_min_u32_e32 v92, v92, v94
	v_cmp_le_u32_e64 s[30:31], s20, v178
	s_nop 1
	v_cndmask_b32_e64 v95, -1, v113, s[30:31]
	v_min_u32_e32 v92, v92, v95
	v_cmp_le_u32_e64 s[26:27], s20, v179
	s_nop 1
	v_cndmask_b32_e64 v93, -1, v114, s[26:27]
	v_min_u32_e32 v92, v92, v93
	v_cmp_le_u32_e64 s[28:29], s20, v180
	s_nop 1
	v_cndmask_b32_e64 v94, -1, v115, s[28:29]
	v_min_u32_e32 v92, v92, v94
	v_cmp_le_u32_e64 s[30:31], s20, v181
	s_nop 1
	v_cndmask_b32_e64 v95, -1, v116, s[30:31]
	v_min_u32_e32 v92, v92, v95
	v_cmp_le_u32_e64 s[26:27], s20, v182
	s_nop 1
	v_cndmask_b32_e64 v93, -1, v117, s[26:27]
	v_min_u32_e32 v92, v92, v93
	v_cmp_le_u32_e64 s[28:29], s20, v183
	s_nop 1
	v_cndmask_b32_e64 v94, -1, v118, s[28:29]
	v_min_u32_e32 v92, v92, v94
	v_cmp_le_u32_e64 s[30:31], s20, v184
	s_nop 1
	v_cndmask_b32_e64 v95, -1, v119, s[30:31]
	v_min_u32_e32 v92, v92, v95
	s_nop 1
	v_min_u32_dpp v92, v92, v92 quad_perm:[1,0,3,2] row_mask:0xf bank_mask:0xf bound_ctrl:1
	s_nop 1
	v_min_u32_dpp v92, v92, v92 quad_perm:[2,3,0,1] row_mask:0xf bank_mask:0xf bound_ctrl:1
	s_nop 1
	v_min_u32_dpp v92, v92, v92 row_half_mirror row_mask:0xf bank_mask:0xf bound_ctrl:1
	s_nop 1
	v_min_u32_dpp v92, v92, v92 row_mirror row_mask:0xf bank_mask:0xf bound_ctrl:1
	s_nop 1
	v_readlane_b32 s13, v92, 0
	v_readlane_b32 s14, v92, 16
	v_readlane_b32 s15, v92, 32
	v_readlane_b32 s17, v92, 48
	s_min_u32 s13, s13, s14
	s_min_u32 s15, s15, s17
	s_min_u32 s13, s13, s15
	s_branch .Lpr_noexact
	s_cmp_eq_u32 s25, 0
	s_cbranch_scc1 .Lpr_nodrop
	s_branch .Lpr_drop

.Lpr_noexact:
	v_mov_b32_e32 v120, 0
	v_cmp_le_u32_e64 s[26:27], s20, v173
	v_cmp_le_u32_e64 s[28:29], s20, v174
	v_cmp_le_u32_e64 s[30:31], s20, v175
	v_addc_co_u32_e64 v120, vcc, 0, v120, s[26:27]
	v_cmp_le_u32_e64 s[26:27], s20, v176
	v_addc_co_u32_e64 v120, vcc, 0, v120, s[28:29]
	v_cmp_le_u32_e64 s[28:29], s20, v177
	v_addc_co_u32_e64 v120, vcc, 0, v120, s[30:31]
	v_cmp_le_u32_e64 s[30:31], s20, v178
	v_addc_co_u32_e64 v120, vcc, 0, v120, s[26:27]
	v_cmp_le_u32_e64 s[26:27], s20, v179
	v_addc_co_u32_e64 v120, vcc, 0, v120, s[28:29]
	v_cmp_le_u32_e64 s[28:29], s20, v180
	v_addc_co_u32_e64 v120, vcc, 0, v120, s[30:31]
	v_cmp_le_u32_e64 s[30:31], s20, v181
	v_addc_co_u32_e64 v120, vcc, 0, v120, s[26:27]
	v_cmp_le_u32_e64 s[26:27], s20, v182
	v_addc_co_u32_e64 v120, vcc, 0, v120, s[28:29]
	v_cmp_le_u32_e64 s[28:29], s20, v183
	v_addc_co_u32_e64 v120, vcc, 0, v120, s[30:31]
	v_cmp_le_u32_e64 s[30:31], s20, v184
	v_addc_co_u32_e64 v120, vcc, 0, v120, s[26:27]
	s_nop 0
	v_addc_co_u32_e64 v120, vcc, 0, v120, s[28:29]
	v_addc_co_u32_e64 v120, vcc, 0, v120, s[30:31]
	v_mov_b32_e32 v122, v120
	s_nop 1
	v_add_u32_dpp v122, v122, v122 row_shr:1 row_mask:0xf bank_mask:0xf bound_ctrl:1
	s_nop 1
	v_add_u32_dpp v122, v122, v122 row_shr:2 row_mask:0xf bank_mask:0xf bound_ctrl:1
	s_nop 1
	v_add_u32_dpp v122, v122, v122 row_shr:4 row_mask:0xf bank_mask:0xf bound_ctrl:1
	s_nop 1
	v_add_u32_dpp v122, v122, v122 row_shr:8 row_mask:0xf bank_mask:0xf bound_ctrl:1
	s_nop 1
	v_add_u32_dpp v122, v122, v122 row_bcast:15 row_mask:0xa bank_mask:0xf
	s_nop 1
	v_add_u32_dpp v122, v122, v122 row_bcast:31 row_mask:0xc bank_mask:0xf
	s_nop 1
	v_sub_u32_e32 v122, v122, v120
	s_mov_b64 s[22:23], exec
	v_cmp_le_u32_e64 s[26:27], s20, v173
	s_mov_b64 exec, s[26:27]
	s_cbranch_execz .Lpr_w0
	v_lshl_add_u32 v93, v122, 2, s9
	v_lshl_add_u32 v94, v122, 1, s10
	ds_write_b32 v93, v161
	ds_write_b16 v94, v142
	v_add_u32_e32 v122, 1, v122

.Lpr_w11:
	s_mov_b64 exec, s[22:23]
	s_bitcmp1_b32 s13, 31
	s_cselect_b32 s17, 0x80000000, -1
	s_xor_b32 s17, s13, s17
	s_mov_b64 exec, s[58:59]
	v_mov_b32_e32 v40, s11
	v_mov_b32_e32 v92, s19
	ds_write_b32 v40, v92
	v_mov_b32_e32 v93, s17
	ds_write_b32 v40, v93 offset:128
	s_mov_b64 exec, s[22:23]
	s_branch .LBB0_143
.Lpr_retry:
	s_cmp_eq_u32 s14, s25
	s_cbranch_scc1 .Lpr_orig
	s_mov_b32 s14, s25
	ds_write_b128 v127, a[206:209]
	s_branch .Lpr_rebin
